# v111 + attention steps 2-4 LDS waits merged (30 to 13 per tile), DMA piece address math shortened via the current tile base, tile-head QK fragment reads batched
# speedup vs baseline: 1.0082x; 1.0082x over previous
; #define ATT_LAS __attribute__((address_space(3)))
; __device__ __forceinline__ int sub1(int a) { int v = a ^ 128; asm volatile("" : "+v"(v)); return v; }
; #define ATT_MFMA(a, b, c) __builtin_amdgcn_mfma_f32_32x32x16_bf16((a), (b), (c), 0, 0, 0)
; #define ATT_STAGE(t, buf) do { _Pragma("unroll") for (int i_ = 0; i_ < 2; ++i_) { \
;         glds16(Kt + (size_t)(t) * 131072, ksrc[i_], (unsigned)__builtin_amdgcn_readfirstlane(ldsb + KBUF + (buf) * 16384 + (w * 2 + i_) * 1024)); \
;         glds16(Vt + (size_t)(t) * 131072, vsrc[i_], (unsigned)__builtin_amdgcn_readfirstlane(ldsb + VBUF + (buf) * 16384 + (w * 2 + i_) * 1024)); } } while (0)
; template <bool C1> __device__ __forceinline__ void qk_issue(f32x16& s0, const ATT_LAS unsigned char* kb, const ATT_LAS unsigned char* qb_, const int (&kaddr)[4]) {
; #pragma unroll
;     for (int i = 0; i < 16; ++i) s0[i] = 0.f;
; #pragma unroll
;     for (int ds = 0; ds < 4; ++ds) {
;         const int ad = C1 ? sub1(kaddr[ds]) : kaddr[ds];
;         const bf16x8 a0 = *(const ATT_LAS bf16x8*)(kb + ad);
;         const bf16x8 qv = *(const ATT_LAS bf16x8*)(qb_ + ad);
;         s0 = ATT_MFMA(a0, qv, s0);
;     }
; __device__ __forceinline__ void attn_unit(ATT_LAS unsigned char* lds, const bf16_t* Qg, const bf16_t* Kg, const bf16_t* Vg, bf16_t* Og, int b, int head, int qb, float lam, const float* subg) {
;     ...
;         if (t + 1 < NT) ATT_STAGE(t + 1, buf ^ 1);
;         const int kvrel = 64 * t - q0 - 32 * wq;
;         if (kvrel <= 31) {
;             const ATT_LAS unsigned char* kb = lds + KBUF + buf * 16384;
;             const ATT_LAS unsigned char* vb = lds + VBUF + buf * 16384;
;             tile_body(kvrel + 63 > 0, kb, vb, qbase, kaddr, vaddr, O1, O2, m1, m2, l1, l2, kvrel, r, h, wsf);
.LBB0_291:
	s_cmp_gt_i32 s80, 31
	s_cbranch_scc1 .Ldma_skip
	s_lshl_b32 s4, s4, 14
	s_add_i32 s81, s4, 0
	v_add_u32_e32 v216, s81, v203
	v_add_u32_e32 v218, s81, v204
	ds_read_b128 v[2:5], v216
	ds_read_b128 v[6:9], v217
	v_add_u32_e32 v220, s81, v205
	ds_read_b128 v[10:13], v218
	ds_read_b128 v[146:149], v219
	v_add_u32_e32 v222, s81, v206
	ds_read_b128 v[150:153], v220
	ds_read_b128 v[154:157], v221
	ds_read_b128 v[158:161], v222
	ds_read_b128 v[162:165], v223
	v_add_u32_e32 v248, s81, v209
	v_add_u32_e32 v249, s81, v210
	v_add_u32_e32 v250, s81, v211
	v_add_u32_e32 v251, s81, v212
	s_cmpk_gt_i32 s80, 0xffc1
	s_cselect_b64 s[36:37], -1, 0
	s_cmpk_lt_i32 s80, 0xffc2
	s_waitcnt lgkmcnt(4)
	v_mfma_f32_32x32x16_bf16 v[170:185], v[2:5], v[6:9], 0
	v_mfma_f32_32x32x16_bf16 v[170:185], v[10:13], v[146:149], v[170:185]
	s_waitcnt lgkmcnt(0)
	v_mfma_f32_32x32x16_bf16 v[170:185], v[150:153], v[154:157], v[170:185]
	v_mfma_f32_32x32x16_bf16 v[170:185], v[158:161], v[162:165], v[170:185]
	s_cbranch_scc0 .Lhead_mask
.LBB0_296:
	s_xor_b32 vcc_lo, s81, 0x4000
	s_add_i32 vcc_lo, vcc_lo, s77
	s_add_i32 m0, vcc_lo, 0x8000
	s_cmp_ge_u32 s79, s76
	s_cbranch_scc1 .Ldma_s1
	global_load_lds_dwordx4 v199, s[94:95]

; #define ATT_LAS __attribute__((address_space(3)))
; __device__ __forceinline__ unsigned cvtpk(float lo, float hi) { unsigned r; asm volatile("v_cvt_pk_bf16_f32 %0, %1, %2" : "=v"(r) : "v"(lo), "v"(hi)); return r; }
; template <bool HAS_PV, bool HAS_QK, bool C1> ...
;     s16x4 vlo[2], vhi[2]; bf16x8 ka, qa;
;     if (HAS_PV) {
; #pragma unroll
;         for (int u = 0; u < 2; ++u) { vlo[u] = vtr(vb + vaddr[0] + u * 512); vhi[u] = vtr(vb + vaddr[1] + u * 512); } }
;     if (HAS_QK) { const int ad = C1 ? sub1(kaddr[0]) : kaddr[0]; ka = *(const ATT_LAS bf16x8*)(kb + ad); qa = *(const ATT_LAS bf16x8*)(qb_ + ad);
; #pragma unroll
;         for (int i = 0; i < 16; ++i) Snext[i] = 0.f; }
;     float sa = 0.f, sb = 0.f;
; #pragma unroll
;     for (int g = 0; g < 4; ++g) {
;         s16x4 nlo[2], nhi[2]; bf16x8 nk, nq;
;         if (g < 3) {
;             if (HAS_PV) {
; #pragma unroll
;                 for (int u = 0; u < 2; ++u) { const int off = (2 * ((g + 1) & 1) + u) * 512 + ((g + 1) >> 1) * 4096; nlo[u] = vtr(vb + vaddr[0] + off); nhi[u] = vtr(vb + vaddr[1] + off); } }
;             if (HAS_QK) { const int ad = C1 ? sub1(kaddr[g + 1]) : kaddr[g + 1]; nk = *(const ATT_LAS bf16x8*)(kb + ad); nq = *(const ATT_LAS bf16x8*)(qb_ + ad); }
;         }
;         if (HAS_PV) { const bf16x8 pa = __builtin_bit_cast(bf16x8, pkin[g >> 1]);
; #pragma unroll
;             for (int u = 0; u < 2; ++u) { const bf16x8 vf = __builtin_shufflevector(vlo[u], vhi[u], 0, 1, 2, 3, 4, 5, 6, 7); Opv[2 * (g & 1) + u] = ATT_MFMA(pa, vf, Opv[2 * (g & 1) + u]); } }
;         if (HAS_QK) Snext = ATT_MFMA(ka, qa, Snext);
; #pragma unroll
;         for (int e = 4 * g; e < 4 * g + 4; e += 2) { Scur[e] = __builtin_amdgcn_exp2f(Scur[e] - m); Scur[e + 1] = __builtin_amdgcn_exp2f(Scur[e + 1] - m); sa += Scur[e]; sb += Scur[e + 1]; }
;         if (g & 1) pkout[g >> 1] = (u32x4){cvtpk(Scur[4 * g - 4], Scur[4 * g - 3]), cvtpk(Scur[4 * g - 2], Scur[4 * g - 1]), cvtpk(Scur[4 * g], Scur[4 * g + 1]), cvtpk(Scur[4 * g + 2], Scur[4 * g + 3])};
;         if (g < 3) {
;             if (HAS_PV) {
; #pragma unroll
;                 for (int u = 0; u < 2; ++u) { vlo[u] = nlo[u]; vhi[u] = nhi[u]; } }
;             if (HAS_QK) { ka = nk; qa = nq; }
;         }
;         __builtin_amdgcn_sched_barrier(0);
;     }
;     l += sa + sb;
;     return sa + sb;
; }
.Lns_311:
	s_xor_b32 vcc_lo, s81, 0x4000
	s_add_i32 m0, vcc_lo, s50
	s_cmp_ge_u32 s79, s76
	s_cbranch_scc1 .Ldma_ns2
	global_load_lds_dwordx4 v200, s[92:93]
.Ldma_ns2:
	v_add_u32_e32 v178, s81, v213
	v_add_u32_e32 v179, s81, v207
	ds_read_b64_tr_b16 v[8:9], v178 offset:34816
	ds_read_b64_tr_b16 v[6:7], v179 offset:32768
	ds_read_b64_tr_b16 v[146:147], v179 offset:33280
	ds_read_b64_tr_b16 v[174:175], v179 offset:33792
	ds_read_b64_tr_b16 v[182:183], v179 offset:34304
	ds_read_b64_tr_b16 v[148:149], v178 offset:35328
	ds_read_b64_tr_b16 v[176:177], v178 offset:35840
	ds_read_b64_tr_b16 v[184:185], v178 offset:36352
	s_waitcnt lgkmcnt(1)
	v_mfma_f32_32x32x16_bf16 v[34:49], v[2:5], v[6:9], v[34:49]
	ds_read_b128 v[6:9], v216 offset:8192
	ds_read_b128 v[150:153], v217
	ds_read_b128 v[186:189], v218 offset:8192
	ds_read_b128 v[226:229], v219
	v_exp_f32_e32 v15, v158
	v_exp_f32_e32 v239, v160
	v_mfma_f32_32x32x16_bf16 v[50:65], v[2:5], v[146:149], v[50:65]
	v_exp_f32_e32 v14, v159
	v_exp_f32_e32 v238, v161
	s_waitcnt lgkmcnt(2)
	v_mfma_f32_32x32x16_bf16 v[146:161], v[6:9], v[150:153], 0
	v_mfma_f32_32x32x16_bf16 v[66:81], v[2:5], v[174:177], v[66:81]
	ds_read_b64_tr_b16 v[6:7], v179 offset:36864
	ds_read_b64_tr_b16 v[8:9], v178 offset:38912
	ds_read_b64_tr_b16 v[176:177], v178 offset:39424
	ds_read_b64_tr_b16 v[174:175], v179 offset:37376
	ds_read_b128 v[230:233], v220 offset:8192
	ds_read_b128 v[234:237], v221
	v_exp_f32_e32 v241, v162
	v_exp_f32_e32 v240, v163
	v_mfma_f32_32x32x16_bf16 v[82:97], v[2:5], v[182:185], v[82:97]
	v_exp_f32_e32 v243, v164
	v_exp_f32_e32 v242, v165
	v_cvt_pk_bf16_f32 v2, v15, v14
	v_cvt_pk_bf16_f32 v3, v239, v238
	v_cvt_pk_bf16_f32 v4, v241, v240
	s_waitcnt lgkmcnt(2)
	v_mfma_f32_32x32x16_bf16 v[146:161], v[186:189], v[226:229], v[146:161]
	v_cvt_pk_bf16_f32 v5, v243, v242
	v_mfma_f32_32x32x16_bf16 v[34:49], v[10:13], v[6:9], v[34:49]
	ds_read_b64_tr_b16 v[6:7], v179 offset:37888
	ds_read_b64_tr_b16 v[8:9], v178 offset:39936
	ds_read_b64_tr_b16 v[164:165], v178 offset:40448
	ds_read_b64_tr_b16 v[162:163], v179 offset:38400
	ds_read_b128 v[182:185], v222 offset:8192
	ds_read_b128 v[186:189], v223
	v_mfma_f32_32x32x16_bf16 v[50:65], v[10:13], v[174:177], v[50:65]
	v_exp_f32_e32 v175, v166
	v_exp_f32_e32 v174, v167
	v_exp_f32_e32 v167, v168
	v_exp_f32_e32 v166, v169
	s_waitcnt lgkmcnt(2)
	v_mfma_f32_32x32x16_bf16 v[146:161], v[230:233], v[234:237], v[146:161]
	v_mfma_f32_32x32x16_bf16 v[66:81], v[10:13], v[6:9], v[66:81]
	v_exp_f32_e32 v169, v170
	v_exp_f32_e32 v168, v171
	v_exp_f32_e32 v171, v172
	v_exp_f32_e32 v170, v173
	v_mfma_f32_32x32x16_bf16 v[82:97], v[10:13], v[162:165], v[82:97]
	v_cvt_pk_bf16_f32 v6, v175, v174
	v_cvt_pk_bf16_f32 v7, v167, v166
	v_cvt_pk_bf16_f32 v8, v169, v168
	v_cvt_pk_bf16_f32 v9, v171, v170
	v_add_f32_e64 v10, v238, v14
	v_add_f32_e64 v11, v239, v15
	s_waitcnt lgkmcnt(0)
	v_mfma_f32_32x32x16_bf16 v[146:161], v[182:185], v[186:189], v[146:161]
	v_add_f32_e64 v10, v240, v10
	v_add_f32_e64 v11, v241, v11
	v_add_f32_e64 v10, v242, v10
	v_add_f32_e64 v11, v243, v11
	v_add_f32_e64 v10, v174, v10
	v_add_f32_e64 v11, v175, v11
	v_add_f32_e32 v10, v166, v10
	v_add_f32_e32 v11, v167, v11
	v_add_f32_e32 v10, v168, v10
	v_add_f32_e32 v11, v169, v11
	v_add_f32_e32 v10, v170, v10
	v_add_f32_e32 v11, v171, v11
	v_add_f32_e32 v10, v10, v11
	v_cmp_nge_f32_e32 vcc, s58, v10
	s_cbranch_vccnz .Lslow_2

; template <bool HAS_PV, bool HAS_QK, bool C1> ...
;     s16x4 vlo[2], vhi[2]; bf16x8 ka, qa;
;     if (HAS_PV) {
; #pragma unroll
;         for (int u = 0; u < 2; ++u) { vlo[u] = vtr(vb + vaddr[0] + u * 512); vhi[u] = vtr(vb + vaddr[1] + u * 512); } }
;     if (HAS_QK) { const int ad = C1 ? sub1(kaddr[0]) : kaddr[0]; ka = *(const ATT_LAS bf16x8*)(kb + ad); qa = *(const ATT_LAS bf16x8*)(qb_ + ad);
; #pragma unroll
;         for (int i = 0; i < 16; ++i) Snext[i] = 0.f; }
;     float sa = 0.f, sb = 0.f;
; #pragma unroll
;     for (int g = 0; g < 4; ++g) {
;         s16x4 nlo[2], nhi[2]; bf16x8 nk, nq;
;         if (g < 3) {
;             if (HAS_PV) {
; #pragma unroll
;                 for (int u = 0; u < 2; ++u) { const int off = (2 * ((g + 1) & 1) + u) * 512 + ((g + 1) >> 1) * 4096; nlo[u] = vtr(vb + vaddr[0] + off); nhi[u] = vtr(vb + vaddr[1] + off); } }
;             if (HAS_QK) { const int ad = C1 ? sub1(kaddr[g + 1]) : kaddr[g + 1]; nk = *(const ATT_LAS bf16x8*)(kb + ad); nq = *(const ATT_LAS bf16x8*)(qb_ + ad); }
;         }
;         if (HAS_PV) { const bf16x8 pa = __builtin_bit_cast(bf16x8, pkin[g >> 1]);
; #pragma unroll
;             for (int u = 0; u < 2; ++u) { const bf16x8 vf = __builtin_shufflevector(vlo[u], vhi[u], 0, 1, 2, 3, 4, 5, 6, 7); Opv[2 * (g & 1) + u] = ATT_MFMA(pa, vf, Opv[2 * (g & 1) + u]); } }
;         if (HAS_QK) Snext = ATT_MFMA(ka, qa, Snext);
; #pragma unroll
;         for (int e = 4 * g; e < 4 * g + 4; e += 2) { Scur[e] = __builtin_amdgcn_exp2f(Scur[e] - m); Scur[e + 1] = __builtin_amdgcn_exp2f(Scur[e + 1] - m); sa += Scur[e]; sb += Scur[e + 1]; }
;         if (g & 1) pkout[g >> 1] = (u32x4){cvtpk(Scur[4 * g - 4], Scur[4 * g - 3]), cvtpk(Scur[4 * g - 2], Scur[4 * g - 1]), cvtpk(Scur[4 * g], Scur[4 * g + 1]), cvtpk(Scur[4 * g + 2], Scur[4 * g + 3])};
;         if (g < 3) {
;             if (HAS_PV) {
; #pragma unroll
;                 for (int u = 0; u < 2; ++u) { vlo[u] = nlo[u]; vhi[u] = nhi[u]; } }
;             if (HAS_QK) { ka = nk; qa = nq; }
;         }
;         __builtin_amdgcn_sched_barrier(0);
;     }
;     l += sa + sb;
;     return sa + sb;
; }
; __device__ __forceinline__ void tile_body(bool MASK, const ATT_LAS unsigned char* kb, const ATT_LAS unsigned char* vb, const ATT_LAS unsigned char* qbase, const int (&kaddr)[4], const int (&vaddr)[2], ...
;     ...
;     apply_mask(MASK, Sa, kvrel + 32, r, h); ls = l1;
.Lns_326:
	s_xor_b32 vcc_lo, s81, 0x4000
	s_add_i32 vcc_lo, vcc_lo, s50
	s_add_i32 m0, vcc_lo, 0x8000
	s_cmp_ge_u32 s79, s76
	s_cbranch_scc1 .Ldma_ns3
	global_load_lds_dwordx4 v201, s[94:95]
.Ldma_ns3:
	ds_read_b64_tr_b16 v[10:11], v179 offset:32768
	ds_read_b64_tr_b16 v[12:13], v178 offset:34816
	ds_read_b64_tr_b16 v[164:165], v178 offset:35328
	ds_read_b64_tr_b16 v[162:163], v179 offset:33280
	s_waitcnt lgkmcnt(0)
	v_mfma_f32_32x32x16_bf16 v[130:145], v[2:5], v[10:13], v[130:145]
	ds_read_b128 v[166:169], v248 offset:8192
	ds_read_b128 v[170:173], v244
	ds_read_b64_tr_b16 v[10:11], v179 offset:33792
	ds_read_b64_tr_b16 v[12:13], v178 offset:35840
	ds_read_b64_tr_b16 v[184:185], v178 offset:36352
	ds_read_b64_tr_b16 v[182:183], v179 offset:34304
	v_mfma_f32_32x32x16_bf16 v[114:129], v[2:5], v[162:165], v[114:129]
	ds_read_b128 v[186:189], v249 offset:8192
	ds_read_b128 v[224:227], v245
	v_exp_f32_e32 v15, v146
	v_exp_f32_e32 v237, v148
	s_waitcnt lgkmcnt(2)
	v_mfma_f32_32x32x16_bf16 v[162:177], v[166:169], v[170:173], 0
	v_exp_f32_e32 v14, v147
	v_exp_f32_e32 v236, v149
	v_mfma_f32_32x32x16_bf16 v[98:113], v[2:5], v[10:13], v[98:113]
	ds_read_b64_tr_b16 v[146:147], v179 offset:36864
	ds_read_b64_tr_b16 v[148:149], v178 offset:38912
	ds_read_b64_tr_b16 v[230:231], v178 offset:39424
	ds_read_b64_tr_b16 v[228:229], v179 offset:37376
	ds_read_b128 v[10:13], v250 offset:8192
	ds_read_b128 v[232:235], v246
	v_mfma_f32_32x32x16_bf16 v[18:33], v[2:5], v[182:185], v[18:33]
	v_exp_f32_e32 v239, v150
	v_exp_f32_e32 v241, v152
	v_exp_f32_e32 v238, v151
	s_waitcnt lgkmcnt(4)
	v_mfma_f32_32x32x16_bf16 v[162:177], v[186:189], v[224:227], v[162:177]
	v_exp_f32_e32 v240, v153
	v_cvt_pk_bf16_f32 v2, v15, v14
	v_cvt_pk_bf16_f32 v3, v237, v236
	v_cvt_pk_bf16_f32 v4, v239, v238
	v_cvt_pk_bf16_f32 v5, v241, v240
	v_mfma_f32_32x32x16_bf16 v[130:145], v[6:9], v[146:149], v[130:145]
	ds_read_b64_tr_b16 v[146:147], v179 offset:37888
	ds_read_b64_tr_b16 v[148:149], v178 offset:39936
	ds_read_b64_tr_b16 v[152:153], v178 offset:40448
	ds_read_b64_tr_b16 v[150:151], v179 offset:38400
	ds_read_b128 v[182:185], v251 offset:8192
	ds_read_b128 v[186:189], v247
	s_waitcnt lgkmcnt(4)
	v_mfma_f32_32x32x16_bf16 v[114:129], v[6:9], v[228:231], v[114:129]
	v_exp_f32_e32 v225, v154
	v_exp_f32_e32 v224, v155
	v_exp_f32_e32 v155, v156
	v_mfma_f32_32x32x16_bf16 v[162:177], v[10:13], v[232:235], v[162:177]
	v_exp_f32_e32 v154, v157
	v_exp_f32_e32 v157, v158
	v_mfma_f32_32x32x16_bf16 v[98:113], v[6:9], v[146:149], v[98:113]
	v_exp_f32_e32 v156, v159
	v_exp_f32_e32 v147, v160
	v_exp_f32_e32 v146, v161
	v_cvt_pk_bf16_f32 v10, v225, v224
	v_cvt_pk_bf16_f32 v11, v155, v154
	s_waitcnt lgkmcnt(0)
	v_mfma_f32_32x32x16_bf16 v[18:33], v[6:9], v[150:153], v[18:33]
	v_cvt_pk_bf16_f32 v12, v157, v156
	v_cvt_pk_bf16_f32 v13, v147, v146
	v_add_f32_e64 v6, v236, v14
	v_add_f32_e64 v7, v237, v15
	v_add_f32_e64 v6, v238, v6
	v_add_f32_e64 v7, v239, v7
	v_mfma_f32_32x32x16_bf16 v[162:177], v[182:185], v[186:189], v[162:177]
	v_add_f32_e64 v6, v240, v6
	v_add_f32_e64 v7, v241, v7
	v_add_f32_e64 v6, v224, v6
	v_add_f32_e64 v7, v225, v7
	v_add_f32_e64 v6, v154, v6
	v_add_f32_e64 v7, v155, v7
	v_add_f32_e32 v6, v156, v6
	v_add_f32_e32 v7, v157, v7
	v_add_f32_e32 v6, v146, v6
	v_add_f32_e32 v7, v147, v7
	v_add_f32_e32 v6, v6, v7
	v_cmp_nge_f32_e32 vcc, s58, v6
	s_cbranch_vccnz .Lslow_3

; template <bool HAS_PV, bool HAS_QK, bool C1> ...
;     s16x4 vlo[2], vhi[2]; bf16x8 ka, qa;
;     if (HAS_PV) {
; #pragma unroll
;         for (int u = 0; u < 2; ++u) { vlo[u] = vtr(vb + vaddr[0] + u * 512); vhi[u] = vtr(vb + vaddr[1] + u * 512); } }
;     if (HAS_QK) { const int ad = C1 ? sub1(kaddr[0]) : kaddr[0]; ka = *(const ATT_LAS bf16x8*)(kb + ad); qa = *(const ATT_LAS bf16x8*)(qb_ + ad);
; #pragma unroll
;         for (int i = 0; i < 16; ++i) Snext[i] = 0.f; }
;     float sa = 0.f, sb = 0.f;
; #pragma unroll
;     for (int g = 0; g < 4; ++g) {
;         s16x4 nlo[2], nhi[2]; bf16x8 nk, nq;
;         if (g < 3) {
;             if (HAS_PV) {
; #pragma unroll
;                 for (int u = 0; u < 2; ++u) { const int off = (2 * ((g + 1) & 1) + u) * 512 + ((g + 1) >> 1) * 4096; nlo[u] = vtr(vb + vaddr[0] + off); nhi[u] = vtr(vb + vaddr[1] + off); } }
;             if (HAS_QK) { const int ad = C1 ? sub1(kaddr[g + 1]) : kaddr[g + 1]; nk = *(const ATT_LAS bf16x8*)(kb + ad); nq = *(const ATT_LAS bf16x8*)(qb_ + ad); }
;         }
;         if (HAS_PV) { const bf16x8 pa = __builtin_bit_cast(bf16x8, pkin[g >> 1]);
; #pragma unroll
;             for (int u = 0; u < 2; ++u) { const bf16x8 vf = __builtin_shufflevector(vlo[u], vhi[u], 0, 1, 2, 3, 4, 5, 6, 7); Opv[2 * (g & 1) + u] = ATT_MFMA(pa, vf, Opv[2 * (g & 1) + u]); } }
;         if (HAS_QK) Snext = ATT_MFMA(ka, qa, Snext);
; #pragma unroll
;         for (int e = 4 * g; e < 4 * g + 4; e += 2) { Scur[e] = __builtin_amdgcn_exp2f(Scur[e] - m); Scur[e + 1] = __builtin_amdgcn_exp2f(Scur[e + 1] - m); sa += Scur[e]; sb += Scur[e + 1]; }
;         if (g & 1) pkout[g >> 1] = (u32x4){cvtpk(Scur[4 * g - 4], Scur[4 * g - 3]), cvtpk(Scur[4 * g - 2], Scur[4 * g - 1]), cvtpk(Scur[4 * g], Scur[4 * g + 1]), cvtpk(Scur[4 * g + 2], Scur[4 * g + 3])};
;         if (g < 3) {
;             if (HAS_PV) {
; #pragma unroll
;                 for (int u = 0; u < 2; ++u) { vlo[u] = nlo[u]; vhi[u] = nhi[u]; } }
;             if (HAS_QK) { ka = nk; qa = nq; }
;         }
;         __builtin_amdgcn_sched_barrier(0);
;     }
;     l += sa + sb;
;     return sa + sb;
; }
; __device__ __forceinline__ void pv_issue(f32x16 (&O)[4], const u32x4 (&pk)[2], const ATT_LAS unsigned char* vb, const int (&vaddr)[2]) {
; #pragma unroll
;     for (int s_ = 0; s_ < 2; ++s_) { const bf16x8 pa = __builtin_bit_cast(bf16x8, pk[s_]);
; #pragma unroll
.Lns_341:
	ds_read_b64_tr_b16 v[8:9], v178 offset:43008
	ds_read_b64_tr_b16 v[6:7], v179 offset:40960
	ds_read_b64_tr_b16 v[146:147], v179 offset:41472
	ds_read_b64_tr_b16 v[150:151], v179 offset:41984
	ds_read_b64_tr_b16 v[154:155], v179 offset:42496
	ds_read_b64_tr_b16 v[148:149], v178 offset:43520
	ds_read_b64_tr_b16 v[152:153], v178 offset:44032
	ds_read_b64_tr_b16 v[156:157], v178 offset:44544
	s_waitcnt lgkmcnt(1)
	v_mfma_f32_32x32x16_bf16 v[34:49], v[2:5], v[6:9], v[34:49]
	v_exp_f32_e32 v15, v162
	v_exp_f32_e32 v14, v163
	v_exp_f32_e32 v163, v164
	v_mfma_f32_32x32x16_bf16 v[50:65], v[2:5], v[146:149], v[50:65]
	v_exp_f32_e32 v162, v165
	v_mfma_f32_32x32x16_bf16 v[66:81], v[2:5], v[150:153], v[66:81]
	ds_read_b64_tr_b16 v[146:147], v179 offset:45056
	ds_read_b64_tr_b16 v[148:149], v178 offset:47104
	ds_read_b64_tr_b16 v[160:161], v178 offset:47616
	ds_read_b64_tr_b16 v[158:159], v179 offset:45568
	v_exp_f32_e32 v165, v166
	v_exp_f32_e32 v164, v167
	v_exp_f32_e32 v167, v168
	s_waitcnt lgkmcnt(2)
	v_mfma_f32_32x32x16_bf16 v[82:97], v[2:5], v[154:157], v[82:97]
	v_exp_f32_e32 v166, v169
	v_cvt_pk_bf16_f32 v6, v15, v14
	v_cvt_pk_bf16_f32 v7, v163, v162
	v_cvt_pk_bf16_f32 v8, v165, v164
	v_cvt_pk_bf16_f32 v9, v167, v166
	v_mfma_f32_32x32x16_bf16 v[34:49], v[10:13], v[146:149], v[34:49]
	ds_read_b64_tr_b16 v[2:3], v179 offset:46080
	ds_read_b64_tr_b16 v[4:5], v178 offset:48128
	ds_read_b64_tr_b16 v[152:153], v178 offset:48640
	ds_read_b64_tr_b16 v[150:151], v179 offset:46592
	v_exp_f32_e32 v147, v170
	v_exp_f32_e32 v146, v171
	v_exp_f32_e32 v149, v172
	s_waitcnt lgkmcnt(0)
	v_mfma_f32_32x32x16_bf16 v[50:65], v[10:13], v[158:161], v[50:65]
	v_exp_f32_e32 v148, v173
	v_mfma_f32_32x32x16_bf16 v[66:81], v[10:13], v[2:5], v[66:81]
	v_exp_f32_e32 v155, v174
	v_exp_f32_e32 v154, v175
	v_exp_f32_e32 v157, v176
	v_mfma_f32_32x32x16_bf16 v[82:97], v[10:13], v[150:153], v[82:97]
	v_add_f32_e64 v10, v162, v14
	v_add_f32_e64 v11, v163, v15
	v_exp_f32_e32 v156, v177
	v_add_f32_e32 v10, v164, v10
	v_add_f32_e32 v11, v165, v11
	v_cvt_pk_bf16_f32 v2, v147, v146
	v_cvt_pk_bf16_f32 v3, v149, v148
	v_cvt_pk_bf16_f32 v4, v155, v154
	v_cvt_pk_bf16_f32 v5, v157, v156
	v_add_f32_e32 v10, v166, v10
	v_add_f32_e32 v11, v167, v11
	v_add_f32_e32 v10, v146, v10
	v_add_f32_e32 v11, v147, v11
	v_add_f32_e32 v10, v148, v10
	v_add_f32_e32 v11, v149, v11
	v_add_f32_e32 v10, v154, v10
	v_add_f32_e32 v11, v155, v11
	v_add_f32_e32 v10, v156, v10
	v_add_f32_e32 v11, v157, v11
	v_add_f32_e32 v10, v10, v11
	v_cmp_nge_f32_e32 vcc, s58, v10
	s_cbranch_vccnz .Lslow_4
	v_add_f32_e32 v224, v181, v10
	ds_read_b64_tr_b16 v[12:13], v178 offset:43008
	ds_read_b64_tr_b16 v[10:11], v179 offset:40960
	ds_read_b64_tr_b16 v[146:147], v179 offset:41472
	ds_read_b64_tr_b16 v[150:151], v179 offset:41984
	ds_read_b64_tr_b16 v[154:155], v179 offset:42496
	ds_read_b64_tr_b16 v[148:149], v178 offset:43520
	ds_read_b64_tr_b16 v[152:153], v178 offset:44032
	ds_read_b64_tr_b16 v[156:157], v178 offset:44544
	ds_read_b64_tr_b16 v[160:161], v178 offset:47104
	ds_read_b64_tr_b16 v[158:159], v179 offset:45056
	ds_read_b64_tr_b16 v[162:163], v179 offset:45568
	ds_read_b64_tr_b16 v[166:167], v179 offset:46080
	ds_read_b64_tr_b16 v[170:171], v179 offset:46592
	ds_read_b64_tr_b16 v[164:165], v178 offset:47616
	ds_read_b64_tr_b16 v[168:169], v178 offset:48128
	s_waitcnt lgkmcnt(7)
	v_mfma_f32_32x32x16_bf16 v[130:145], v[6:9], v[10:13], v[130:145]
	v_mfma_f32_32x32x16_bf16 v[114:129], v[6:9], v[146:149], v[114:129]
	v_mfma_f32_32x32x16_bf16 v[98:113], v[6:9], v[150:153], v[98:113]
	v_mfma_f32_32x32x16_bf16 v[18:33], v[6:9], v[154:157], v[18:33]
	ds_read_b64_tr_b16 v[172:173], v178 offset:48640
	s_waitcnt lgkmcnt(0)
	v_mfma_f32_32x32x16_bf16 v[130:145], v[2:5], v[158:161], v[130:145]
	v_mfma_f32_32x32x16_bf16 v[114:129], v[2:5], v[162:165], v[114:129]
	v_mfma_f32_32x32x16_bf16 v[98:113], v[2:5], v[166:169], v[98:113]
	v_mfma_f32_32x32x16_bf16 v[18:33], v[2:5], v[170:173], v[18:33]
	s_add_i32 s80, s80, 64
	s_add_u32 s94, s94, 0x20000
	s_addc_u32 s95, s95, 0
	s_waitcnt vmcnt(0)
	s_add_u32 s92, s92, 0x20000
	s_addc_u32 s93, s93, 0
	s_cmp_eq_u32 s76, s79
	v_subrev_u32_e32 v214, 64, v214
	s_barrier
	s_cbranch_scc0 .LBB0_289
	s_branch .LBB0_352
